# next-layer weight conversion moved off the 128 overloaded workgroups onto the other 384 (virtual grid of 384 in the convert loops)
# baseline (speedup 1.0000x reference)
.LBB0_919:
	v_readlane_b32 s0, v215, 25
	s_add_i32 s2, s0, 1
	v_readlane_b32 s1, v215, 26
	v_writelane_b32 v215, s2, 32
	s_cmp_eq_u32 s0, 3
	s_nop 0
	v_writelane_b32 v215, s3, 33
	s_cbranch_scc1 .LBB0_999
	v_readlane_b32 s98, v216, 52
	v_readlane_b32 s99, v216, 58
	s_cmpk_lg_u32 s33, 0x200
	s_cbranch_scc1 .Lcvb_keep
	s_and_b32 s98, s85, 63
	s_lshr_b32 s99, s85, 6
	s_cmpk_lt_u32 s98, 16
	s_cbranch_scc1 .LBB0_999
	s_mul_i32 s99, s99, 48
	s_add_i32 s98, s98, s99
	s_sub_i32 s98, s98, 16
	s_lshl_b32 s98, s98, 8
	s_mov_b32 s99, 0x18000
.Lcvb_keep:
	v_readlane_b32 s16, v215, 6
	s_mov_b64 s[0:1], 0
	v_readlane_b32 s30, v215, 20
	v_readlane_b32 s17, v215, 7
	v_readlane_b32 s18, v215, 8
	v_readlane_b32 s19, v215, 9
	v_readlane_b32 s20, v215, 10
	v_readlane_b32 s21, v215, 11
	v_readlane_b32 s22, v215, 12
	v_readlane_b32 s23, v215, 13
	v_readlane_b32 s24, v215, 14
	v_readlane_b32 s25, v215, 15
	v_readlane_b32 s26, v215, 16
	v_readlane_b32 s27, v215, 17
	v_readlane_b32 s28, v215, 18
	v_readlane_b32 s29, v215, 19
	v_readlane_b32 s31, v215, 21
	s_add_u32 s2, s30, s0
	s_addc_u32 s3, s31, s1
	v_readlane_b32 s0, v215, 32
	v_readlane_b32 s16, v216, 20
	v_readlane_b32 s1, v215, 33
	s_mov_b32 s4, s0
	v_readlane_b32 s20, v216, 24
	v_readlane_b32 s21, v216, 25
	v_readlane_b32 s22, v216, 26
	v_readlane_b32 s23, v216, 27
	v_readlane_b32 s24, v216, 28
	v_readlane_b32 s25, v216, 29
	v_readlane_b32 s26, v216, 30
	v_readlane_b32 s27, v216, 31
	s_mul_i32 s1, s4, 0x1da0000
	v_readlane_b32 s28, v216, 32
	v_readlane_b32 s29, v216, 33
	v_readlane_b32 s30, v216, 34
	v_readlane_b32 s31, v216, 35
	s_mov_b64 s[20:21], s[24:25]
	s_mul_hi_u32 s0, s0, 0x1da0000
	s_add_u32 s4, s20, s1
	s_addc_u32 s5, s21, s0
	v_readlane_b32 s0, v215, 29
	v_readlane_b32 s1, v215, 30
	s_and_b64 s[0:1], s[0:1], exec
	s_cselect_b32 s0, 0x1db60000, 0
	s_add_u32 s2, s2, s0
	v_mov_b32_e32 v0, v111
	s_mov_b32 s0, s98
	s_addc_u32 s3, s3, 0
	v_readlane_b32 s17, v216, 21
	v_add_u32_e32 v4, s0, v0
	s_mov_b32 s0, 0x50000
	v_cmp_gt_i32_e32 vcc, s0, v4
	v_readlane_b32 s18, v216, 22
	v_readlane_b32 s19, v216, 23
	s_mov_b64 s[22:23], s[26:27]
	s_mov_b64 s[24:25], s[28:29]
	s_mov_b64 s[26:27], s[30:31]
	s_and_saveexec_b64 s[6:7], vcc
	s_cbranch_execz .LBB0_939
	s_mul_i32 s0, s98, 2
	s_mov_b64 s[8:9], 0
	s_nop 0
	v_lshl_add_u32 v5, v0, 1, s0
	s_mov_b32 s0, s99
	s_lshl_b32 s0, s0, 1
	s_branch .LBB0_923
.LBB0_922:
	s_or_b64 exec, exec, s[10:11]
	s_waitcnt vmcnt(0)
	v_cvt_pk_bf16_f32 v12, v1, v3
	v_ashrrev_i32_e32 v3, 31, v2
	s_mov_b32 s1, s99
	v_lshlrev_b64 v[2:3], 11, v[2:3]
	v_lshl_add_u64 v[2:3], s[2:3], 0, v[2:3]
	v_add_u32_e32 v4, s1, v4
	s_mov_b32 s1, 0x4ffff
	v_ashrrev_i32_e32 v1, 31, v0
	v_cmp_lt_i32_e32 vcc, s1, v4
	v_cvt_pk_bf16_f32 v13, v7, v6
	v_cvt_pk_bf16_f32 v14, v9, v8
	v_cvt_pk_bf16_f32 v15, v11, v10
	v_lshl_add_u64 v[0:1], v[0:1], 1, v[2:3]
	s_or_b64 s[8:9], vcc, s[8:9]
	v_add_u32_e32 v5, s0, v5
	global_store_dwordx4 v[0:1], v[12:15], off
	s_andn2_b64 exec, exec, s[8:9]
	s_cbranch_execz .LBB0_939

.LBB0_939:
	s_or_b64 exec, exec, s[6:7]
	v_readlane_b32 s0, v215, 32
	v_readlane_b32 s1, v215, 33
	s_mov_b32 s1, s87
	v_writelane_b32 v215, s0, 32
	v_mov_b32_e32 v0, v111
	s_nop 0
	v_writelane_b32 v215, s1, 33
	s_mov_b32 s0, s98
	s_nop 1
	v_add_u32_e32 v4, s0, v0
	s_mov_b32 s0, 0xa0000
	v_cmp_gt_i32_e32 vcc, s0, v4
	s_and_saveexec_b64 s[6:7], vcc
	s_mov_b32 s16, s99
	s_mov_b32 s17, 0x66666667
	s_movk_i32 s18, 0x600
	s_cbranch_execz .LBB0_942
	s_add_u32 s8, s2, 0x500000
	s_addc_u32 s9, s3, 0
	s_mov_b64 s[10:11], 0

.LBB0_942:
	s_movk_i32 s83, 0x600
	s_or_b64 exec, exec, s[6:7]
	v_mov_b32_e32 v0, v111
	s_mov_b32 s0, s98
	s_nop 1
	v_add_u32_e32 v12, s0, v0
	s_mov_b32 s0, 0x10000
	v_cmp_gt_i32_e32 vcc, s0, v12
	s_and_saveexec_b64 s[4:5], vcc
	s_cbranch_execz .LBB0_977
	v_readlane_b32 s16, v216, 20
	v_readlane_b32 s0, v215, 32
	v_readlane_b32 s20, v216, 24
	v_readlane_b32 s21, v216, 25
	v_readlane_b32 s22, v216, 26
	v_readlane_b32 s23, v216, 27
	v_readlane_b32 s24, v216, 28
	v_readlane_b32 s25, v216, 29
	v_readlane_b32 s26, v216, 30
	v_readlane_b32 s27, v216, 31
	v_readlane_b32 s1, v215, 33
	v_readlane_b32 s28, v216, 32
	v_readlane_b32 s29, v216, 33
	v_readlane_b32 s30, v216, 34
	v_readlane_b32 s31, v216, 35
	s_mov_b64 s[20:21], s[24:25]
	s_lshl_b64 s[0:1], s[0:1], 20
	s_mov_b64 s[22:23], s[26:27]
	s_mov_b64 s[24:25], s[28:29]
	s_mov_b64 s[26:27], s[30:31]
	v_readlane_b32 s17, v216, 21
	v_readlane_b32 s18, v216, 22
	v_readlane_b32 s19, v216, 23
	s_add_u32 s6, s26, s0
	s_addc_u32 s7, s27, s1
	v_readlane_b32 s16, v216, 36
	v_readlane_b32 s18, v216, 38
	v_readlane_b32 s19, v216, 39
	s_add_u32 s8, s18, s0
	s_addc_u32 s9, s19, s1
	v_readlane_b32 s17, v216, 37
	s_add_u32 s10, s2, 0xf00000
	s_addc_u32 s11, s3, 0
	s_mov_b64 s[16:17], 0
	v_readlane_b32 s20, v216, 40
	v_readlane_b32 s21, v216, 41
	v_readlane_b32 s22, v216, 42
	v_readlane_b32 s23, v216, 43
	v_readlane_b32 s24, v216, 44
	v_readlane_b32 s25, v216, 45
	v_readlane_b32 s26, v216, 46
	v_readlane_b32 s27, v216, 47
	v_readlane_b32 s28, v216, 48
	v_readlane_b32 s29, v216, 49
	v_readlane_b32 s30, v216, 50
	v_readlane_b32 s31, v216, 51
	s_branch .LBB0_945
.LBB0_944:
	s_or_b64 exec, exec, s[18:19]
	global_load_dword v7, v[8:9], off
	s_waitcnt vmcnt(6)
	v_cvt_pk_bf16_f32 v4, v3, v13
	v_ashrrev_i32_e32 v3, 31, v2
	s_mov_b32 s0, s99
	v_lshlrev_b64 v[2:3], 8, v[2:3]
	v_lshl_add_u64 v[2:3], s[10:11], 0, v[2:3]
	v_add_u32_e32 v12, s0, v12
	s_mov_b32 s0, 0xffff
	v_cmp_lt_i32_e32 vcc, s0, v12
	s_waitcnt vmcnt(4)
	v_cvt_pk_bf16_f32 v5, v14, v15
	s_waitcnt vmcnt(2)
	v_cvt_pk_bf16_f32 v6, v16, v17
	v_lshl_add_u64 v[0:1], v[0:1], 1, v[2:3]
	s_or_b64 s[16:17], vcc, s[16:17]
	s_waitcnt vmcnt(0)
	v_cvt_pk_bf16_f32 v7, v18, v7
	global_store_dwordx4 v[0:1], v[4:7], off
	s_andn2_b64 exec, exec, s[16:17]
	s_cbranch_execz .LBB0_977

.LBB0_977:
	s_or_b64 exec, exec, s[4:5]
	v_mov_b32_e32 v0, v111
	s_mov_b32 s0, s98
	s_nop 1
	v_add_u32_e32 v1, s0, v0
	s_mov_b32 s0, 0x9000
	v_cmp_gt_i32_e32 vcc, s0, v1
	s_and_saveexec_b64 s[4:5], vcc
	s_mov_b32 s36, s99
	s_movk_i32 s37, 0xc00
	s_mov_b32 s38, 0x8fff
	s_movk_i32 s39, 0x60
	s_cbranch_execz .LBB0_980
	v_readlane_b32 s8, v215, 32
	v_readlane_b32 s16, v216, 36
	s_mul_i32 s1, s8, 0x120000
	v_readlane_b32 s26, v216, 46
	s_mul_hi_u32 s0, s8, 0x120000
	v_readlane_b32 s27, v216, 47
	s_add_u32 s6, s26, s1
	s_mul_i32 s86, s8, 0x180
	v_readlane_b32 s24, v216, 44
	s_addc_u32 s7, s27, s0
	s_lshl_b64 s[0:1], s[86:87], 2
	v_readlane_b32 s9, v215, 33
	v_readlane_b32 s25, v216, 45
	s_add_u32 s8, s24, s0
	s_addc_u32 s9, s25, s1
	s_mul_i32 s0, s98, 2
	s_movk_i32 s1, 0x180
	v_readlane_b32 s17, v216, 37
	s_add_u32 s10, s2, 0x1000000
	v_lshl_add_u32 v2, v0, 1, s0
	v_mul_lo_u32 v0, v0, s1
	s_mul_i32 s1, s98, 0x180
	s_addc_u32 s11, s3, 0
	s_lshl_b32 s0, s36, 1
	v_add_u32_e32 v0, s1, v0
	s_mov_b64 s[16:17], 0
	v_readlane_b32 s18, v216, 38
	v_readlane_b32 s19, v216, 39
	v_readlane_b32 s20, v216, 40
	v_readlane_b32 s21, v216, 41
	v_readlane_b32 s22, v216, 42
	v_readlane_b32 s23, v216, 43
	v_readlane_b32 s28, v216, 48
	v_readlane_b32 s29, v216, 49
	v_readlane_b32 s30, v216, 50
	v_readlane_b32 s31, v216, 51

.LBB0_980:
	s_or_b64 exec, exec, s[4:5]
	v_readlane_b32 s0, v215, 32
	v_readlane_b32 s1, v215, 33
	v_readlane_b32 s16, v216, 36
	s_lshl_b64 s[4:5], s[0:1], 20
	v_readlane_b32 s30, v216, 50
	v_mov_b32_e32 v0, v111
	s_mov_b32 s0, s98
	v_readlane_b32 s31, v216, 51
	s_add_u32 s6, s30, s4
	s_addc_u32 s7, s31, s5
	v_add_u32_e32 v6, s0, v0
	v_cmp_gt_i32_e32 vcc, s61, v6
	v_readlane_b32 s17, v216, 37
	v_readlane_b32 s18, v216, 38
	v_readlane_b32 s19, v216, 39
	v_readlane_b32 s20, v216, 40
	v_readlane_b32 s21, v216, 41
	v_readlane_b32 s22, v216, 42
	v_readlane_b32 s23, v216, 43
	v_readlane_b32 s24, v216, 44
	v_readlane_b32 s25, v216, 45
	v_readlane_b32 s26, v216, 46
	v_readlane_b32 s27, v216, 47
	v_readlane_b32 s28, v216, 48
	v_readlane_b32 s29, v216, 49
	s_and_saveexec_b64 s[8:9], vcc
	s_mov_b32 s36, s99
	s_movk_i32 s37, 0x7fff
	s_cbranch_execz .LBB0_983
	v_readlane_b32 s0, v215, 32
	v_readlane_b32 s1, v215, 33
	s_lshl_b32 s86, s0, 8
	v_readlane_b32 s16, v216, 36
	s_lshl_b64 s[0:1], s[86:87], 2
	v_readlane_b32 s28, v216, 48
	v_readlane_b32 s29, v216, 49
	s_add_u32 s10, s28, s0
	s_addc_u32 s11, s29, s1
	v_readlane_b32 s17, v216, 37
	v_readlane_b32 s18, v216, 38
	v_readlane_b32 s19, v216, 39
	s_add_u32 s16, s2, 0x1090000
	s_addc_u32 s17, s3, 0
	s_mov_b64 s[18:19], 0
	v_readlane_b32 s20, v216, 40
	v_readlane_b32 s21, v216, 41
	v_readlane_b32 s22, v216, 42
	v_readlane_b32 s23, v216, 43
	v_readlane_b32 s24, v216, 44
	v_readlane_b32 s25, v216, 45
	v_readlane_b32 s26, v216, 46
	v_readlane_b32 s27, v216, 47
	v_readlane_b32 s30, v216, 50
	v_readlane_b32 s31, v216, 51

.LBB0_983:
	s_or_b64 exec, exec, s[8:9]
	v_mov_b32_e32 v0, v111
	s_mov_b32 s0, s98
	s_nop 1
	v_add_u32_e32 v0, s0, v0
	v_cmp_gt_i32_e32 vcc, s61, v0
	s_and_saveexec_b64 s[8:9], vcc
	s_mov_b32 s18, s99
	s_movk_i32 s19, 0x7fff
	s_cbranch_execz .LBB0_986
	s_add_u32 s10, s2, 0x1110000
	s_addc_u32 s11, s3, 0
	s_mov_b64 s[16:17], 0

.LBB0_986:
	s_or_b64 exec, exec, s[8:9]
	v_mov_b32_e32 v0, v111
	s_mov_b32 s0, s98
	s_nop 1
	v_add_u32_e32 v0, s0, v0
	s_mov_b32 s0, 0x20000
	v_cmp_gt_i32_e32 vcc, s0, v0
	s_and_saveexec_b64 s[6:7], vcc
	s_mov_b32 s36, s99
	s_mov_b32 s37, 0x1ffff
	s_cbranch_execz .LBB0_989
	v_readlane_b32 s16, v215, 6
	s_lshl_b64 s[0:1], s[4:5], 2
	v_readlane_b32 s18, v215, 8
	v_readlane_b32 s19, v215, 9
	s_add_u32 s8, s18, s0
	s_addc_u32 s9, s19, s1
	v_readlane_b32 s17, v215, 7
	s_add_u32 s10, s2, 0x1190000
	s_addc_u32 s11, s3, 0
	s_mov_b64 s[16:17], 0
	v_readlane_b32 s20, v215, 10
	v_readlane_b32 s21, v215, 11
	v_readlane_b32 s22, v215, 12
	v_readlane_b32 s23, v215, 13
	v_readlane_b32 s24, v215, 14
	v_readlane_b32 s25, v215, 15
	v_readlane_b32 s26, v215, 16
	v_readlane_b32 s27, v215, 17
	v_readlane_b32 s28, v215, 18
	v_readlane_b32 s29, v215, 19
	v_readlane_b32 s30, v215, 20
	v_readlane_b32 s31, v215, 21

.LBB0_989:
	s_or_b64 exec, exec, s[6:7]
	v_readlane_b32 s0, v215, 32
	v_readlane_b32 s1, v215, 33
	v_mov_b32_e32 v0, v111
	s_lshl_b64 s[6:7], s[0:1], 19
	s_mov_b32 s0, s98
	s_nop 1
	v_add_u32_e32 v0, s0, v0
	s_mov_b32 s0, 0x10000
	v_cmp_gt_i32_e32 vcc, s0, v0
	s_and_saveexec_b64 s[8:9], vcc
	s_mov_b32 s36, s99
	s_mov_b32 s37, 0xffff
	s_cbranch_execz .LBB0_992
	v_readlane_b32 s16, v215, 6
	s_lshl_b64 s[0:1], s[6:7], 2
	v_readlane_b32 s20, v215, 10
	v_readlane_b32 s21, v215, 11
	s_add_u32 s10, s20, s0
	s_addc_u32 s11, s21, s1
	v_readlane_b32 s17, v215, 7
	v_readlane_b32 s18, v215, 8
	v_readlane_b32 s19, v215, 9
	s_add_u32 s16, s2, 0x1390000
	s_addc_u32 s17, s3, 0
	s_mov_b64 s[18:19], 0
	v_readlane_b32 s22, v215, 12
	v_readlane_b32 s23, v215, 13
	v_readlane_b32 s24, v215, 14
	v_readlane_b32 s25, v215, 15
	v_readlane_b32 s26, v215, 16
	v_readlane_b32 s27, v215, 17
	v_readlane_b32 s28, v215, 18
	v_readlane_b32 s29, v215, 19
	v_readlane_b32 s30, v215, 20
	v_readlane_b32 s31, v215, 21

.LBB0_992:
	s_or_b64 exec, exec, s[8:9]
	v_mov_b32_e32 v0, v111
	s_mov_b32 s0, s98
	s_nop 1
	v_add_u32_e32 v0, s0, v0
	s_mov_b32 s0, 0x10000
	v_cmp_gt_i32_e32 vcc, s0, v0
	s_and_saveexec_b64 s[8:9], vcc
	s_mov_b32 s36, s99
	s_mov_b32 s37, 0xffff
	s_cbranch_execz .LBB0_995
	v_readlane_b32 s16, v215, 6
	s_lshl_b64 s[0:1], s[6:7], 2
	v_readlane_b32 s22, v215, 12
	v_readlane_b32 s23, v215, 13
	s_add_u32 s6, s22, s0
	s_addc_u32 s7, s23, s1
	v_readlane_b32 s17, v215, 7
	s_add_u32 s10, s2, 0x1490000
	s_addc_u32 s11, s3, 0
	s_mov_b64 s[16:17], 0
	v_readlane_b32 s18, v215, 8
	v_readlane_b32 s19, v215, 9
	v_readlane_b32 s20, v215, 10
	v_readlane_b32 s21, v215, 11
	v_readlane_b32 s24, v215, 14
	v_readlane_b32 s25, v215, 15
	v_readlane_b32 s26, v215, 16
	v_readlane_b32 s27, v215, 17
	v_readlane_b32 s28, v215, 18
	v_readlane_b32 s29, v215, 19
	v_readlane_b32 s30, v215, 20
	v_readlane_b32 s31, v215, 21

.LBB0_995:
	s_or_b64 exec, exec, s[8:9]
	v_mov_b32_e32 v0, v111
	s_mov_b32 s0, s98
	s_nop 1
	v_add_u32_e32 v0, s0, v0
	s_mov_b32 s0, 0x20000
	v_cmp_gt_i32_e32 vcc, s0, v0
	s_and_saveexec_b64 s[6:7], vcc
	s_mov_b32 s10, s99
	s_mov_b32 s11, 0x1ffff
	s_cbranch_execz .LBB0_998
	v_readlane_b32 s16, v215, 6
	s_lshl_b64 s[0:1], s[4:5], 2
	v_readlane_b32 s24, v215, 14
	v_readlane_b32 s25, v215, 15
	s_add_u32 s4, s24, s0
	s_addc_u32 s5, s25, s1
	s_add_u32 s2, s2, 0x1590000
	s_addc_u32 s3, s3, 0
	s_mov_b64 s[8:9], 0
	v_readlane_b32 s17, v215, 7
	v_readlane_b32 s18, v215, 8
	v_readlane_b32 s19, v215, 9
	v_readlane_b32 s20, v215, 10
	v_readlane_b32 s21, v215, 11
	v_readlane_b32 s22, v215, 12
	v_readlane_b32 s23, v215, 13
	v_readlane_b32 s26, v215, 16
	v_readlane_b32 s27, v215, 17
	v_readlane_b32 s28, v215, 18
	v_readlane_b32 s29, v215, 19
	v_readlane_b32 s30, v215, 20
	v_readlane_b32 s31, v215, 21
